# k21: k16 + attention copy-2 K/V LDS-write ladder counts vmcnt(7,5,4) on the load-issued path instead of draining to vmcnt(0)
# speedup vs baseline: 1.0020x; 1.0020x over previous
; __device__ __forceinline__ void partialSM(f32x16& p0, f32x16& p1, float& m_reg, float& mn, float& alpha) {
;   constexpr float C = SCALE * 1.4426950408889634f;
;   float pmax = p0[0]; for (int r = 1; r < 16; ++r) pmax = fmaxf(pmax, p0[r]); for (int r = 0; r < 16; ++r) pmax = fmaxf(pmax, p1[r]);
;   { auto rr = __builtin_amdgcn_permlane32_swap(__float_as_uint(pmax), __float_as_uint(pmax), false, false);
;     pmax = fmaxf(__uint_as_float(rr[0]), __uint_as_float(rr[1])); }
;   if (__builtin_expect(__all(pmax - m_reg <= THR / SCALE), 1)) { mn = m_reg; alpha = 1.f; }
;   else { mn = fmaxf(m_reg, pmax); alpha = __builtin_amdgcn_exp2f((m_reg - mn) * C); m_reg = mn; }
;   float mnC = -mn * C;
;   for (int r = 0; r < 16; ++r) p0[r] = fmaf(p0[r], C, mnC); for (int r = 0; r < 16; ++r) p1[r] = fmaf(p1[r], C, mnC);
;   for (int r = 0; r < 16; ++r) p0[r] = __builtin_amdgcn_exp2f(p0[r]);
; }
; __device__ __forceinline__ void finishSM(f32x16& p0, f32x16& p1, float alpha, float& l_reg, bf16x8& pa0, bf16x8& pa1, bf16x8& pa2, bf16x8& pa3) {
;   for (int r = 0; r < 16; ++r) p1[r] = __builtin_amdgcn_exp2f(p1[r]);
;   float ps = 0; for (int r = 0; r < 16; ++r) ps += p0[r]; for (int r = 0; r < 16; ++r) ps += p1[r];
;   { auto rr = __builtin_amdgcn_permlane32_swap(__float_as_uint(ps), __float_as_uint(ps), false, false);
;     ps = __uint_as_float(rr[0]) + __uint_as_float(rr[1]); }
;   l_reg = l_reg * alpha + ps;
;     ...
;   PK4(p0, 0, pa0); PK4(p0, 8, pa1); PK4(p1, 0, pa2); PK4(p1, 8, pa3);
;     ...
; }
; __device__ __forceinline__ void qkt(f32x16& p0, f32x16& p1, const char* Ks, const bf16x8* qr, int r32, int hi) {
;   p0 = f32x16{}; p1 = f32x16{};
;   for (int d0 = 0; d0 < 8; ++d0) { int cb = (d0 * 16 + hi * 8) * 2;
;     bf16x8 b0 = *reinterpret_cast<const bf16x8*>(Ks + KSWZ(r32, cb));
;     bf16x8 b1 = *reinterpret_cast<const bf16x8*>(Ks + KSWZ(32 + r32, cb));
;     p0 = __builtin_amdgcn_mfma_f32_32x32x16_bf16(b0, qr[d0], p0, 0, 0, 0);
;     p1 = __builtin_amdgcn_mfma_f32_32x32x16_bf16(b1, qr[d0], p1, 0, 0, 0); }
; }
; __device__ __forceinline__ int v_st(int k, int c) { const int kk = (k & ~0xC) | ((k & 4) << 1) | ((k & 8) >> 1); return ((kk >> 3) * 4 + (c >> 5)) * 512 + ((kk & 7) * 32 + (c & 31)) * 2; }
; __device__ __forceinline__ int v_rd_base(int lane) { return ((lane & 3) << 3) | (((lane >> 2) & 3) << 6) | (((lane >> 4) & 1) << 5) | (((lane >> 5) & 1) << 8); }
.LBB0_265:
	ds_read_b64_tr_b16 v[216:217], v190 offset:0
	ds_read_b64_tr_b16 v[218:219], v190 offset:0x800
	ds_read_b64_tr_b16 v[220:221], v190 offset:0x1000
	ds_read_b64_tr_b16 v[222:223], v190 offset:0x1800
	ds_read_b64_tr_b16 v[224:225], v190 offset:0x2000
	ds_read_b64_tr_b16 v[226:227], v190 offset:0x2800
	ds_read_b64_tr_b16 v[228:229], v190 offset:0x3000
	ds_read_b64_tr_b16 v[230:231], v190 offset:0x3800
	s_waitcnt lgkmcnt(0)
	s_nop 0
	v_mfma_f32_32x32x16_bf16 v[0:15], v[160:163], v[216:219], v[0:15]
	ds_read_b64_tr_b16 v[216:217], v190 offset:0x200
	ds_read_b64_tr_b16 v[218:219], v190 offset:0xa00
	v_mfma_f32_32x32x16_bf16 v[0:15], v[164:167], v[220:223], v[0:15]
	ds_read_b64_tr_b16 v[220:221], v190 offset:0x1200
	ds_read_b64_tr_b16 v[222:223], v190 offset:0x1a00
	v_mfma_f32_32x32x16_bf16 v[0:15], v[168:171], v[224:227], v[0:15]
	ds_read_b64_tr_b16 v[224:225], v190 offset:0x2200
	ds_read_b64_tr_b16 v[226:227], v190 offset:0x2a00
	v_mfma_f32_32x32x16_bf16 v[0:15], v[172:175], v[228:231], v[0:15]
	ds_read_b64_tr_b16 v[228:229], v190 offset:0x3200
	ds_read_b64_tr_b16 v[230:231], v190 offset:0x3a00
	s_waitcnt lgkmcnt(0)
	v_mfma_f32_32x32x16_bf16 v[48:63], v[160:163], v[216:219], v[48:63]
	ds_read_b64_tr_b16 v[216:217], v190 offset:0x400
	ds_read_b64_tr_b16 v[218:219], v190 offset:0xc00
	v_mfma_f32_32x32x16_bf16 v[48:63], v[164:167], v[220:223], v[48:63]
	ds_read_b64_tr_b16 v[220:221], v190 offset:0x1400
	ds_read_b64_tr_b16 v[222:223], v190 offset:0x1c00
	v_mfma_f32_32x32x16_bf16 v[48:63], v[168:171], v[224:227], v[48:63]
	ds_read_b64_tr_b16 v[224:225], v190 offset:0x2400
	ds_read_b64_tr_b16 v[226:227], v190 offset:0x2c00
	v_mfma_f32_32x32x16_bf16 v[48:63], v[172:175], v[228:231], v[48:63]
	ds_read_b64_tr_b16 v[228:229], v190 offset:0x3400
	ds_read_b64_tr_b16 v[230:231], v190 offset:0x3c00
	s_waitcnt lgkmcnt(0)
	v_mfma_f32_32x32x16_bf16 v[32:47], v[160:163], v[216:219], v[32:47]
	ds_read_b64_tr_b16 v[216:217], v190 offset:0x600
	ds_read_b64_tr_b16 v[218:219], v190 offset:0xe00
	v_mfma_f32_32x32x16_bf16 v[32:47], v[164:167], v[220:223], v[32:47]
	ds_read_b64_tr_b16 v[220:221], v190 offset:0x1600
	ds_read_b64_tr_b16 v[222:223], v190 offset:0x1e00
	v_mfma_f32_32x32x16_bf16 v[32:47], v[168:171], v[224:227], v[32:47]
	ds_read_b64_tr_b16 v[224:225], v190 offset:0x2600
	ds_read_b64_tr_b16 v[226:227], v190 offset:0x2e00
	v_mfma_f32_32x32x16_bf16 v[32:47], v[172:175], v[228:231], v[32:47]
	ds_read_b64_tr_b16 v[228:229], v190 offset:0x3600
	ds_read_b64_tr_b16 v[230:231], v190 offset:0x3e00
	s_waitcnt lgkmcnt(0)
	v_mfma_f32_32x32x16_bf16 v[16:31], v[160:163], v[216:219], v[16:31]
	v_max_f32_e32 v160, v80, v81
	v_max3_f32 v160, v160, v82, v83
	v_max3_f32 v160, v160, v84, v85
	v_max3_f32 v160, v160, v86, v87
	v_max3_f32 v160, v160, v88, v89
	v_max3_f32 v160, v160, v90, v91
	v_max3_f32 v160, v160, v92, v93
	v_mfma_f32_32x32x16_bf16 v[16:31], v[164:167], v[220:223], v[16:31]
	v_max3_f32 v160, v160, v94, v95
	v_max3_f32 v160, v160, v64, v65
	v_max3_f32 v160, v160, v66, v67
	v_max3_f32 v160, v160, v68, v69
	v_max3_f32 v160, v160, v70, v71
	v_max3_f32 v160, v160, v72, v73
	v_max3_f32 v160, v160, v74, v75
	v_max3_f32 v160, v160, v76, v77
	v_mfma_f32_32x32x16_bf16 v[16:31], v[168:171], v[224:227], v[16:31]
	v_max3_f32 v160, v160, v78, v79
	v_mov_b32_e32 v161, v160
	s_nop 1
	v_permlane32_swap_b32_e32 v160, v161
	v_max_f32_e32 v160, v160, v161
	v_sub_f32_e32 v161, v160, v213
	v_cmp_ge_f32_e32 vcc, s71, v161
	v_max_f32_e32 v161, v213, v160
	v_mfma_f32_32x32x16_bf16 v[16:31], v[172:175], v[228:231], v[16:31]
	v_sub_f32_e32 v160, v213, v161
	v_mul_f32_e32 v160, 0x3e0293ee, v160
	v_exp_f32_e32 v160, v160
	s_cmp_eq_u64 vcc, exec
	s_cselect_b64 s[38:39], -1, 0
	s_barrier
	s_waitcnt vmcnt(4)
	v_cndmask_b32_e64 v160, v160, 1.0, s[38:39]
	v_cmp_gt_f32_e32 vcc, 1.0, v160
	s_cmp_lg_u64 s[42:43], 0
	s_cbranch_scc1 .Lkv2_lastw
	s_waitcnt vmcnt(7)
	ds_write_b128 v192, v[144:147] offset:16384
	s_waitcnt vmcnt(5)
	ds_write_b128 v193, v[156:159] offset:16384
	ds_write_b128 v199, v[148:151] offset:32768
	s_waitcnt vmcnt(4)
	ds_write_b128 v200, v[152:155] offset:32768
	s_branch .Lkv2_wdone
.Lkv2_lastw:
	s_waitcnt vmcnt(3)
	ds_write_b128 v192, v[144:147] offset:16384
	s_waitcnt vmcnt(1)
	ds_write_b128 v193, v[156:159] offset:16384
	ds_write_b128 v199, v[148:151] offset:32768
	s_waitcnt vmcnt(0)
	ds_write_b128 v200, v[152:155] offset:32768
.Lkv2_wdone:
	s_cbranch_vccz .LBB0_269
	s_and_saveexec_b64 s[44:45], s[36:37]
	ds_write_b32 v188, v160 offset:128
	s_or_b64 exec, exec, s[44:45]
	s_waitcnt lgkmcnt(0)
	v_add_u32_e32 v156, v187, v176
	ds_read_b128 v[144:147], v156 offset:224
	ds_read_b128 v[148:151], v156 offset:192
	ds_read_b128 v[152:155], v156 offset:160
	ds_read_b128 v[156:159], v156 offset:128
	s_waitcnt lgkmcnt(3)
	v_pk_mul_f32 v[12:13], v[12:13], v[144:145]
	s_waitcnt lgkmcnt(2)
	v_pk_mul_f32 v[8:9], v[8:9], v[148:149]
	s_waitcnt lgkmcnt(1)
	v_pk_mul_f32 v[4:5], v[4:5], v[152:153]
	v_pk_mul_f32 v[14:15], v[14:15], v[146:147]
	v_pk_mul_f32 v[10:11], v[10:11], v[150:151]
	v_pk_mul_f32 v[6:7], v[6:7], v[154:155]
	s_waitcnt lgkmcnt(0)
	v_pk_mul_f32 v[2:3], v[2:3], v[158:159]
	v_pk_mul_f32 v[0:1], v[0:1], v[156:157]
	v_pk_mul_f32 v[60:61], v[60:61], v[144:145]
	v_pk_mul_f32 v[56:57], v[56:57], v[148:149]
	v_pk_mul_f32 v[52:53], v[52:53], v[152:153]
	v_pk_mul_f32 v[62:63], v[62:63], v[146:147]
	v_pk_mul_f32 v[58:59], v[58:59], v[150:151]
	v_pk_mul_f32 v[54:55], v[54:55], v[154:155]
	v_pk_mul_f32 v[50:51], v[50:51], v[158:159]
	v_pk_mul_f32 v[48:49], v[48:49], v[156:157]
	v_pk_mul_f32 v[44:45], v[44:45], v[144:145]
	v_pk_mul_f32 v[40:41], v[40:41], v[148:149]
	v_pk_mul_f32 v[36:37], v[36:37], v[152:153]
	v_pk_mul_f32 v[46:47], v[46:47], v[146:147]
	v_pk_mul_f32 v[42:43], v[42:43], v[150:151]
	v_pk_mul_f32 v[38:39], v[38:39], v[154:155]
	v_pk_mul_f32 v[34:35], v[34:35], v[158:159]
	v_pk_mul_f32 v[32:33], v[32:33], v[156:157]
	v_pk_mul_f32 v[28:29], v[28:29], v[144:145]
	v_pk_mul_f32 v[24:25], v[24:25], v[148:149]
	v_pk_mul_f32 v[20:21], v[20:21], v[152:153]
	v_pk_mul_f32 v[30:31], v[30:31], v[146:147]
	v_pk_mul_f32 v[26:27], v[26:27], v[150:151]
	v_pk_mul_f32 v[22:23], v[22:23], v[154:155]
	v_pk_mul_f32 v[18:19], v[18:19], v[158:159]
	v_pk_mul_f32 v[16:17], v[16:17], v[156:157]
